# E_GU tiles remapped so each XCD owns whole row panels; grid barriers after out-proj and after gate/up replaced by XCD-local 64-workgroup barriers (arrive/release counters on separate cache lines), gua
# speedup vs baseline: 1.0324x; 1.0274x over previous
.Lg_skip:
	s_add_u32 s96, s0, 0xe0
	s_addc_u32 s97, s1, 0
	s_add_u32 s26, s4, 0x200
	s_addc_u32 s27, s5, 0
	s_add_u32 s34, s4, 0x1000
	s_addc_u32 s35, s5, 0
	s_add_u32 s2, s4, 0x1100
	s_addc_u32 s3, s5, 0
	v_writelane_b32 v254, s2, 2
	s_load_dwordx16 s[36:51], s[0:1], 0x40
	s_load_dwordx16 s[80:95], s[0:1], 0x0
	v_writelane_b32 v254, s3, 3
	s_add_u32 s2, s4, 0x1200
	s_addc_u32 s3, s5, 0
	s_add_u32 s22, s4, 0x1300
	s_addc_u32 s23, s5, 0
	v_writelane_b32 v254, s2, 4
	s_cmp_eq_u32 s14, 15
	v_mbcnt_lo_u32_b32 v0, -1, 0
	v_writelane_b32 v254, s3, 5
	s_cselect_b64 s[2:3], -1, 0
	v_writelane_b32 v254, s2, 6
	s_cmp_eq_u32 s14, 14
	s_waitcnt lgkmcnt(0)
	v_writelane_b32 v255, s80, 0
	v_writelane_b32 v254, s3, 7
	s_cselect_b64 s[2:3], -1, 0
	v_writelane_b32 v254, s2, 8
	s_cmp_eq_u32 s14, 13
	v_writelane_b32 v255, s81, 1
	v_writelane_b32 v254, s3, 9
	s_cselect_b64 s[2:3], -1, 0
	v_writelane_b32 v254, s2, 10
	s_cmp_eq_u32 s14, 12
	v_writelane_b32 v255, s82, 2
	v_writelane_b32 v254, s3, 11
	s_cselect_b64 s[2:3], -1, 0
	v_writelane_b32 v254, s2, 12
	s_cmp_eq_u32 s14, 11
	v_writelane_b32 v255, s83, 3
	v_writelane_b32 v254, s3, 13
	s_cselect_b64 s[2:3], -1, 0
	v_writelane_b32 v254, s2, 14
	s_cmp_eq_u32 s14, 10
	v_writelane_b32 v255, s84, 4
	v_writelane_b32 v254, s3, 15
	s_cselect_b64 s[2:3], -1, 0
	v_writelane_b32 v254, s2, 16
	s_cmp_eq_u32 s14, 9
	v_writelane_b32 v255, s85, 5
	v_writelane_b32 v254, s3, 17
	s_cselect_b64 s[2:3], -1, 0
	v_writelane_b32 v254, s2, 18
	s_cmp_eq_u32 s14, 8
	v_writelane_b32 v255, s86, 6
	v_writelane_b32 v254, s3, 19
	s_cselect_b64 s[2:3], -1, 0
	v_writelane_b32 v254, s2, 20
	s_cmp_eq_u32 s14, 7
	v_writelane_b32 v255, s87, 7
	v_writelane_b32 v254, s3, 21
	s_cselect_b64 s[2:3], -1, 0
	v_writelane_b32 v254, s2, 22
	s_cmp_eq_u32 s14, 6
	v_writelane_b32 v255, s88, 8
	v_writelane_b32 v254, s3, 23
	s_cselect_b64 s[2:3], -1, 0
	v_writelane_b32 v254, s2, 24
	s_cmp_eq_u32 s14, 5
	v_writelane_b32 v255, s89, 9
	v_writelane_b32 v254, s3, 25
	s_cselect_b64 s[2:3], -1, 0
	v_writelane_b32 v254, s2, 26
	s_cmp_eq_u32 s14, 4
	v_writelane_b32 v255, s90, 10
	v_writelane_b32 v254, s3, 27
	s_cselect_b64 s[2:3], -1, 0
	v_writelane_b32 v254, s2, 28
	s_cmp_eq_u32 s14, 3
	v_writelane_b32 v255, s91, 11
	v_writelane_b32 v254, s3, 29
	s_cselect_b64 s[2:3], -1, 0
	v_writelane_b32 v254, s2, 30
	s_cmp_eq_u32 s14, 2
	v_writelane_b32 v255, s92, 12
	v_writelane_b32 v254, s3, 31
	s_cselect_b64 s[2:3], -1, 0
	v_writelane_b32 v254, s2, 32
	s_cmp_eq_u32 s14, 1
	v_writelane_b32 v255, s93, 13
	v_writelane_b32 v254, s3, 33
	s_cselect_b64 s[2:3], -1, 0
	v_writelane_b32 v254, s2, 34
	s_cmp_eq_u32 s14, 0
	v_writelane_b32 v255, s94, 14
	v_writelane_b32 v254, s3, 35
	s_cselect_b64 s[2:3], -1, 0
	v_writelane_b32 v254, s2, 36
	v_writelane_b32 v255, s95, 15
	s_mov_b32 s82, s15
	v_writelane_b32 v254, s3, 37
	s_lshl_b32 s2, s14, 8
	s_add_u32 s2, s4, s2
	s_addc_u32 s3, s5, 0
	s_add_u32 s8, s2, 0x1400
	s_addc_u32 s9, s3, 0
	v_writelane_b32 v254, s8, 38
	s_add_u32 s2, s2, 0x2400
	s_addc_u32 s3, s3, 0
	v_writelane_b32 v254, s9, 39
	v_writelane_b32 v254, s2, 40
	s_load_dwordx4 s[8:11], s[0:1], 0xc0
	v_mov_b32_e32 v117, 0
	v_writelane_b32 v254, s3, 41
	s_add_u32 s2, s4, 0x3400
	s_addc_u32 s3, s5, 0
	v_writelane_b32 v254, s2, 42
	s_movk_i32 s76, 0x5000
	s_mov_b32 s75, 0x43800000
	v_writelane_b32 v254, s3, 43
	s_add_u32 s2, s4, 0x3500
	s_addc_u32 s3, s5, 0
	v_writelane_b32 v254, s2, 44
	v_mov_b32_e32 v212, 0x358637bd
	v_mbcnt_hi_u32_b32 v213, -1, v0
	v_writelane_b32 v254, s3, 45
	s_add_u32 s2, s36, 0x5a000
	v_writelane_b32 v254, s36, 46
	s_addc_u32 s3, s37, 0
	v_mov_b32_e32 v118, 0x33800000
	v_writelane_b32 v254, s37, 47
	v_writelane_b32 v254, s38, 48
	v_writelane_b32 v254, s39, 49
	v_writelane_b32 v254, s40, 50
	v_writelane_b32 v254, s41, 51
	v_writelane_b32 v254, s42, 52
	v_writelane_b32 v254, s43, 53
	v_writelane_b32 v254, s44, 54
	v_writelane_b32 v254, s45, 55
	v_writelane_b32 v254, s46, 56
	v_writelane_b32 v254, s47, 57
	v_writelane_b32 v254, s48, 58
	v_writelane_b32 v254, s49, 59
	v_writelane_b32 v254, s50, 60
	v_writelane_b32 v254, s51, 61
	s_load_dwordx16 s[48:63], s[0:1], 0x80
	v_writelane_b32 v254, s2, 62
	v_mov_b32_e32 v242, 0x3c0881c4
	v_mov_b32_e32 v219, 0xbab64f3b
	v_writelane_b32 v254, s3, 63
	s_waitcnt lgkmcnt(0)
	v_writelane_b32 v255, s48, 16
	v_mov_b32_e32 v218, 0xb0000
	v_mov_b32_e32 v220, 0xf149f2ca
	v_writelane_b32 v255, s49, 17
	v_writelane_b32 v255, s50, 18
	v_writelane_b32 v255, s51, 19
	v_writelane_b32 v255, s52, 20
	v_writelane_b32 v255, s53, 21
	v_writelane_b32 v255, s54, 22
	v_writelane_b32 v255, s55, 23
	v_writelane_b32 v255, s56, 24
	v_writelane_b32 v255, s57, 25
	v_writelane_b32 v255, s58, 26
	v_writelane_b32 v255, s59, 27
	v_writelane_b32 v255, s60, 28
	v_writelane_b32 v255, s61, 29
	v_writelane_b32 v255, s62, 30
	v_writelane_b32 v255, s63, 31
	v_writelane_b32 v255, s8, 32
	v_mov_b32_e32 v120, 0x11fe0
	v_mov_b32_e32 v221, 0xffffe400
	v_writelane_b32 v255, s9, 33
	v_writelane_b32 v255, s10, 34
	v_writelane_b32 v255, s11, 35
	v_writelane_b32 v255, s22, 36
	v_mov_b32_e32 v222, 0x1c00
	v_mov_b32_e32 v123, 0x3f2aaaaa
	v_writelane_b32 v255, s23, 37
	v_writelane_b32 v255, s26, 38
	v_not_b32_e32 v223, 63
	v_not_b32_e32 v224, 31
	v_writelane_b32 v255, s27, 39
	v_writelane_b32 v255, s34, 40
	v_mov_b32_e32 v225, 0x7fc00000
	v_mov_b32_e32 v249, 0xb00000
	v_writelane_b32 v255, s35, 41
	s_movk_i32 s79, 0x3000
	s_movk_i32 s78, 0x7000
	s_movk_i32 s77, 0xfefe
	s_mov_b32 s31, 0
	s_mov_b64 s[66:67], 0x2400
	s_mov_b64 s[28:29], 0x4000
	s_mov_b64 s[44:45], 0x2000
	s_mov_b64 s[24:25], 0x80
	s_movk_i32 s33, 0x6000
	v_writelane_b32 v255, s82, 42
	v_writelane_b32 v255, s31, 52
	s_mov_b32 s2, 1
	v_writelane_b32 v255, s2, 53
	s_branch .LBB0_22

.LBB0_116:
	s_andn2_b64 vcc, exec, s[0:1]
	s_cbranch_vccnz .LBB0_143
	s_load_dword s0, s[96:97], 0x0
	s_and_b32 s22, s74, 7
	s_waitcnt lgkmcnt(0)
	s_lshr_b32 s13, s0, 6
	v_cvt_f32_u32_e32 v0, s13
	s_sub_i32 s1, 0, s13
	s_add_i32 s0, s13, 43
	v_rcp_iflag_f32_e32 v0, v0
	s_nop 0
	v_mul_f32_e32 v0, 0x4f7ffffe, v0
	v_cvt_u32_f32_e32 v0, v0
	s_nop 0
	v_readfirstlane_b32 s8, v0
	s_mul_i32 s1, s1, s8
	s_mul_hi_u32 s1, s8, s1
	s_add_i32 s8, s8, s1
	s_mul_hi_u32 s1, s0, s8
	s_mul_i32 s8, s1, s13
	s_sub_i32 s0, s0, s8
	s_add_i32 s9, s1, 1
	s_sub_i32 s8, s0, s13
	s_cmp_ge_u32 s0, s13
	s_cselect_b32 s1, s9, s1
	s_cselect_b32 s0, s8, s0
	s_add_i32 s8, s1, 1
	s_cmp_ge_u32 s0, s13
	s_cselect_b32 s23, s8, s1
	s_mul_i32 s23, s23, 6
	s_cmp_ge_u32 s22, s23
	s_cbranch_scc1 .LBB0_143
	s_cmp_eq_u32 s13, 8
	s_cbranch_scc0 .Lgu_orig1
	s_lshr_b32 s22, s74, 3
	s_movk_i32 s23, 0x108
	s_mov_b64 s[8:9], 0
	s_mul_hi_u32 s1, s22, 0x2aaaaaab
	s_mul_i32 s15, s1, 6
	s_sub_i32 s15, s22, s15
	s_lshl_b32 s0, s15, 3
	s_and_b32 s15, s74, 7
	s_or_b32 s0, s0, s15
	s_lshl_b32 s0, s0, 7
	s_lshl_b32 s14, s1, 7
	s_add_i32 s22, s22, 64
	s_mov_b64 s[8:9], -1
	s_branch .LBB0_124
.Lgu_orig1:
	s_lshl_b32 s0, s74, 4
	s_ashr_i32 s30, s74, 6
	s_and_b32 s34, s0, 0x380
	s_mov_b64 s[8:9], 0
	s_branch .LBB0_120

.LBB0_139:
	s_cmp_eq_u32 s13, 8
	s_cbranch_scc0 .Lgu_orig2
	s_mul_hi_u32 s1, s22, 0x2aaaaaab
	s_mul_i32 s15, s1, 6
	s_sub_i32 s15, s22, s15
	s_lshl_b32 s38, s15, 3
	s_and_b32 s15, s74, 7
	s_or_b32 s38, s38, s15
	s_lshl_b32 s38, s38, 7
	s_lshl_b32 s35, s1, 7
	s_add_i32 s22, s22, 64
	s_mov_b64 s[16:17], -1
	s_mov_b64 s[10:11], -1
	s_branch .LBB0_128

.LBB0_354:
	s_mov_b32 s99, 0x7fffffff
	s_cmp_eq_u32 s27, 5
	s_cbranch_scc0 .Lh_n5
	s_lshr_b32 s98, s74, 3
	s_cmp_lt_u32 s98, 8
	s_cbranch_scc1 .Lh_norm

.LBB0_508:
	s_cmp_gt_u32 s6, 2
	s_cbranch_scc1 .Lcen_done
	s_getreg_b32 s98, hwreg(HW_REG_XCC_ID, 0, 4)
	s_add_i32 s98, s98, 1
	s_cmp_eq_u32 s6, 0
	s_cbranch_scc0 .Lcen_1
	s_cmp_lt_u32 s82, 8
	s_cbranch_scc0 .Lcen_done
	s_lshl_b32 s99, s82, 2
	v_mov_b32_e32 v0, s99
	v_mov_b32_e32 v1, s98
	global_store_dword v0, v1, s[4:5]
	s_branch .Lcen_done
.Lcen_1:
	s_cmp_eq_u32 s6, 1
	s_cbranch_scc0 .Lcen_2
	s_and_b32 s99, s82, 7
	s_lshl_b32 s99, s99, 2
	v_mov_b32_e32 v0, s99
	global_load_dword v1, v0, s[4:5]
	s_waitcnt vmcnt(0)
	v_readfirstlane_b32 s99, v1
	s_cmp_eq_u32 s99, s98
	s_cbranch_scc1 .Lcen_done
	v_mov_b32_e32 v0, 64
	v_mov_b32_e32 v1, 1
	global_atomic_add v0, v1, s[4:5]
	s_branch .Lcen_done
.Lcen_2:
	v_mov_b32_e32 v0, 64
	global_load_dword v1, v0, s[4:5]
	s_waitcnt vmcnt(0)
	v_readfirstlane_b32 s99, v1
	s_nop 0
	v_writelane_b32 v255, s99, 53

.Lchk_skip:
	s_load_dword s98, s[96:97], 0x0
	s_waitcnt lgkmcnt(0)
	s_cmp_eq_u32 s98, 0x200
	s_cbranch_scc0 .LBB0_509
	v_readlane_b32 s98, v255, 53
	s_cmp_eq_u32 s98, 0
	s_cbranch_scc0 .LBB0_509
	s_add_i32 s99, s6, -3
	s_cmp_lt_i32 s99, 0
	s_cbranch_scc1 .LBB0_509
	s_mul_i32 s98, s99, 37
	s_lshr_b32 s98, s98, 8
	s_mul_i32 s98, s98, 7
	s_sub_i32 s99, s99, s98
	s_cmp_eq_u32 s99, 3
	s_cbranch_scc0 .Llb_chk
	s_waitcnt vmcnt(0) lgkmcnt(0)
	s_barrier
	s_mov_b64 s[0:1], 0
	s_branch .Llong21
.Llb_chk:
	s_cmp_eq_u32 s99, 4
	s_cbranch_scc1 .Llb_do
	s_cmp_eq_u32 s99, 5
	s_cbranch_scc0 .LBB0_509
.Llb_do:
	s_waitcnt vmcnt(0) lgkmcnt(0)
	s_barrier
	v_readlane_b32 s8, v255, 52
	s_add_i32 s8, s8, 1
	v_writelane_b32 v255, s8, 52
	s_mov_b64 s[10:11], exec
	v_readlane_b32 s2, v254, 0
	v_readlane_b32 s3, v254, 1
	s_and_b64 s[2:3], s[10:11], s[2:3]
	s_mov_b64 exec, s[2:3]
	s_cbranch_execz .Llb_done
	s_and_b32 s9, s82, 7
	s_lshl_b32 s9, s9, 8
	s_addk_i32 s9, 0x480
	v_mov_b32_e32 v0, s9
	v_mov_b32_e32 v1, 1
	global_atomic_add v2, v0, v1, s[4:5] sc0
	buffer_inv sc1
	v_add_u32_e32 v0, 0x2000, v0
	s_waitcnt vmcnt(0)
	v_readfirstlane_b32 s9, v2
	s_add_i32 s9, s9, 1
	s_lshl_b32 s13, s8, 6
	s_cmp_eq_u32 s9, s13
	s_cbranch_scc0 .Llb_wait
	global_atomic_add v0, v1, s[4:5]
	s_branch .Llb_done
.Llb_wait:
	s_mov_b32 s12, 0
.Llb_spin:
	global_load_dword v1, v0, s[4:5] sc1
	s_waitcnt vmcnt(0)
	v_readfirstlane_b32 s9, v1
	s_cmp_ge_u32 s9, s8
	s_cbranch_scc1 .Llb_done
	s_sleep 1
	s_add_i32 s12, s12, 1
	s_cmp_lt_u32 s12, 0x1000
	s_cbranch_scc1 .Llb_spin
.Llb_done:
	s_mov_b64 exec, s[10:11]
	s_barrier
	s_mov_b64 s[0:1], 0
	s_branch .Llong21
